# variant: no static priority raise (noprio+novalu only)
# baseline (speedup 1.0000x reference)
; #define LAS __attribute__((address_space(3)))
; __device__ __forceinline__ unsigned xb_add(unsigned* p, unsigned v) { return __hip_atomic_fetch_add(p, v, __ATOMIC_RELAXED, __HIP_MEMORY_SCOPE_AGENT); }
; __device__ __forceinline__ unsigned xb_xcc_id() { return (unsigned)__builtin_amdgcn_s_getreg((3 << 11) | 20) & 0xFu; }
; __device__ __forceinline__ XcdBarrier xcd_barrier_post(unsigned* bar, volatile LAS unsigned* st) {
;     XcdBarrier b; b.bar = bar; b.x = xb_xcc_id(); b.st = st;
;     if (threadIdx.x == 0) (void)xb_add(&bar[XB_XCNT(b.x)], 1u);
;     return b;
; __global__ void __launch_bounds__(NTHR, 2) hybrid_fwd(Args args) {
;     ...
;     const int tid = threadIdx.x, lane = tid & 63, wave = __builtin_amdgcn_readfirstlane(tid >> 6);
;     const int G = gridDim.x, gw = blockIdx.x * NWAVES + wave, ngw = G * NWAVES;
;     for (int u = tid; u < (LDS_BYTES - LDSCTL_OFF) / 4; u += NTHR) ((LAS unsigned*)(lds + LDSCTL_OFF))[u] = 0u;
;     __syncthreads();
;     unsigned* ctl = (unsigned*)(p.ws + WS_CTL);
;     XcdBarrier bar = xcd_barrier_post(ctl + CW_BAR + args.li * XCD_BAR_WORDS, (volatile LAS unsigned*)(lds + MISC_OFF) + 8);
_Z10hybrid_fwd4Args:
	s_load_dword s92, s[0:1], 0xd0
	v_writelane_b32 v240, s2, 0
	v_readfirstlane_b32 s2, v0
	v_lshl_add_u32 v1, v0, 2, 0
	v_add_u32_e32 v2, 0x20000, v1
	v_writelane_b32 v240, s2, 1
	s_add_u32 s2, s0, 0xd0
	s_addc_u32 s3, s1, 0
	v_writelane_b32 v240, s2, 2
	v_mov_b32_e32 v3, 0
	ds_write2st64_b32 v2, v3, v3 offset1:8
	ds_write2st64_b32 v2, v3, v3 offset0:16 offset1:24
	v_writelane_b32 v240, s3, 3
	v_or_b32_e32 v2, 0x800, v0
	s_mov_b64 s[2:3], -1
	s_and_saveexec_b64 s[4:5], s[2:3]
	v_lshl_add_u32 v4, v2, 2, 0
	v_add_u32_e32 v4, 0x20000, v4
	ds_write_b32 v4, v3
	s_or_b64 exec, exec, s[4:5]
	s_load_dwordx4 s[40:43], s[0:1], 0xc0
	s_and_saveexec_b64 s[4:5], s[2:3]
	s_add_i32 s2, 0, 0x20000
	v_lshl_add_u32 v2, v2, 2, s2
	v_mov_b32_e32 v3, 0
	ds_write_b32 v2, v3 offset:2048
	s_or_b64 exec, exec, s[4:5]
	v_or_b32_e32 v2, 0xc00, v0
	v_cmp_gt_u32_e64 s[2:3], 7, 6
	v_cmp_gt_u32_e64 s[6:7], 7, 5
	s_and_saveexec_b64 s[4:5], s[6:7]
	v_lshl_add_u32 v3, v2, 2, 0
	v_add_u32_e32 v3, 0x20000, v3
	v_mov_b32_e32 v4, 0
	ds_write_b32 v3, v4
	s_or_b64 exec, exec, s[4:5]
	s_load_dwordx16 s[44:59], s[0:1], 0x80
	s_and_saveexec_b64 s[4:5], s[2:3]
	s_add_i32 s2, 0, 0x20000
	v_lshl_add_u32 v2, v2, 2, s2
	v_mov_b32_e32 v3, 0
	ds_write_b32 v2, v3 offset:2048
	s_or_b64 exec, exec, s[4:5]
	s_load_dwordx16 s[4:19], s[0:1], 0x0
	s_waitcnt lgkmcnt(0)
	s_mul_i32 s2, s42, 0xd80
	s_ashr_i32 s3, s2, 31
	s_lshl_b64 s[2:3], s[2:3], 2
	s_add_u32 s2, s58, s2
	v_writelane_b32 v240, s4, 4
	s_addc_u32 s3, s59, s3
	s_add_u32 s2, s2, 0x4000
	v_writelane_b32 v240, s5, 5
	v_writelane_b32 v240, s6, 6
	v_writelane_b32 v240, s7, 7
	v_writelane_b32 v240, s8, 8
	v_writelane_b32 v240, s9, 9
	v_writelane_b32 v240, s10, 10
	v_writelane_b32 v240, s11, 11
	v_writelane_b32 v240, s12, 12
	v_writelane_b32 v240, s13, 13
	v_writelane_b32 v240, s14, 14
	v_writelane_b32 v240, s15, 15
	v_writelane_b32 v240, s16, 16
	v_writelane_b32 v240, s17, 17
	v_writelane_b32 v240, s18, 18
	v_writelane_b32 v240, s19, 19
	s_addc_u32 s3, s3, 0
	v_writelane_b32 v240, s2, 20
	s_barrier
	s_nop 0
	v_writelane_b32 v240, s3, 21
	s_getreg_b32 s2, hwreg(HW_REG_XCC_ID, 0, 4)
	s_and_b32 s2, s2, 15
	v_writelane_b32 v240, s2, 22
	v_cmp_eq_u32_e64 s[4:5], 0, v0
	s_mov_b64 s[2:3], exec
	s_nop 0
	v_writelane_b32 v240, s4, 23
	s_nop 1
	v_writelane_b32 v240, s5, 24
	s_and_b64 s[4:5], s[2:3], s[4:5]
	s_mov_b64 exec, s[4:5]
	s_cbranch_execz .LBB0_11
	s_mov_b64 s[4:5], exec
	v_mbcnt_lo_u32_b32 v2, s4, 0
	v_mbcnt_hi_u32_b32 v2, s5, v2
	v_cmp_eq_u32_e32 vcc, 0, v2
	s_and_b64 s[6:7], exec, vcc
	s_mov_b64 exec, s[6:7]
	s_cbranch_execz .LBB0_11
	v_readlane_b32 s6, v240, 22
	s_bcnt1_i32_b64 s4, s[4:5]
	s_lshl_b32 s6, s6, 8
	v_mov_b32_e32 v3, s4
	v_readlane_b32 s4, v240, 20
	v_mov_b32_e32 v2, s6
	v_readlane_b32 s5, v240, 21
	s_nop 4
	global_atomic_add v2, v3, s[4:5] offset:1024

; __device__ __forceinline__ TrDesc p0_item(const Params& p, int it) {
;     ...
;     const int mat = r / 32, rr = r % 32, kb_ = rr / 8, nb_ = rr % 8;
;     const float* W = (mat < 8 ? p.rg_w_x : p.rg_w_a) + (size_t)(mat & 7) * 65536;
;     return TrDesc{W + (size_t)(64 * kb_) * 256 + 32 * nb_, WRG + (size_t)mat * 65536 + (size_t)(32 * nb_) * 256 + 64 * kb_, nullptr, 256, 256};
.Lcv_back_7:
.Lcv_job_rgx:
	s_load_dwordx2 s[60:61], s[24:25], 0x78
	s_load_dwordx2 s[62:63], s[24:25], 0xb8
	s_mov_b32 s6, 0x400
	s_mov_b32 s7, 0x200
	s_mov_b32 s75, 8
	s_sub_i32 s9, s18, 384
	s_cmp_lt_u32 s9, 64
	s_cselect_b32 s74, 1, 0
	s_and_b32 s9, s9, 63
	s_lshr_b32 s10, s9, 3
	s_bfe_u32 s21, s9, 0x20001
	s_and_b32 s26, s9, 1
	s_lshl_b32 s11, s10, 18
	s_lshl_b32 s27, s21, 16
	s_add_u32 s11, s11, s27
	s_lshl_b32 s27, s26, 9
	s_add_u32 s11, s11, s27
	s_lshl_b32 s23, s10, 17
	s_lshl_b32 s27, s26, 16
	s_add_u32 s23, s23, s27
	s_lshl_b32 s27, s21, 7
	s_add_u32 s23, s23, s27
	s_mov_b32 s70, 0
	s_mov_b32 s71, 0
	s_mov_b32 s72, 0
	s_mov_b32 s73, 0
	s_waitcnt lgkmcnt(0)
	s_add_u32 s60, s60, s11
	s_addc_u32 s61, s61, 0
	s_add_u32 s62, s62, 0x2f600000
	s_addc_u32 s63, s63, 0
	s_add_u32 s62, s62, s23
	s_addc_u32 s63, s63, 0
	s_lshl_b32 s26, s7, 5
	s_add_u32 s64, s62, s26
	s_addc_u32 s65, s63, 0
	s_add_u32 s66, s64, s26
	s_addc_u32 s67, s65, 0
	s_add_u32 s68, s66, s26
	s_addc_u32 s69, s67, 0
	s_mov_b32 s8, 0
	s_branch .Lcv_run
.Lcv_back_8:
.Lcv_job_rga:
	s_load_dwordx2 s[60:61], s[24:25], 0x88
	s_load_dwordx2 s[62:63], s[24:25], 0xb8
	s_mov_b32 s6, 0x400
	s_mov_b32 s7, 0x200
	s_mov_b32 s75, 9
	s_sub_i32 s9, s18, 448
	s_cmp_lt_u32 s9, 64
	s_cselect_b32 s74, 1, 0
	s_and_b32 s9, s9, 63
	s_lshr_b32 s10, s9, 3
	s_bfe_u32 s21, s9, 0x20001
	s_and_b32 s26, s9, 1
	s_lshl_b32 s11, s10, 18
	s_lshl_b32 s27, s21, 16
	s_add_u32 s11, s11, s27
	s_lshl_b32 s27, s26, 9
	s_add_u32 s11, s11, s27
	s_lshl_b32 s23, s10, 17
	s_lshl_b32 s27, s26, 16
	s_add_u32 s23, s23, s27
	s_lshl_b32 s27, s21, 7
	s_add_u32 s23, s23, s27
	s_mov_b32 s70, 0
	s_mov_b32 s71, 0
	s_mov_b32 s72, 0
	s_mov_b32 s73, 0
	s_waitcnt lgkmcnt(0)
	s_add_u32 s60, s60, s11
	s_addc_u32 s61, s61, 0
	s_add_u32 s62, s62, 0x2f700000
	s_addc_u32 s63, s63, 0
	s_add_u32 s62, s62, s23
	s_addc_u32 s63, s63, 0
	s_lshl_b32 s26, s7, 5
	s_add_u32 s64, s62, s26
	s_addc_u32 s65, s63, 0
	s_add_u32 s66, s64, s26
	s_addc_u32 s67, s65, 0
	s_add_u32 s68, s66, s26
	s_addc_u32 s69, s67, 0
	s_mov_b32 s8, 0
	s_branch .Lcv_run
